# v9 + rw2 state/X exports coalesced: per-wave padded LDS staging tile (pitch 144 B), four 1 KiB global_store_dwordx4 per chunk instead of eight row-strided dwordx2
# speedup vs baseline: 1.0411x; 1.0333x over previous
; #define GAS __attribute__((address_space(1)))
; #define RW2_BAR() do { __builtin_amdgcn_s_barrier(); asm volatile("" ::: "memory"); } while (0)
; __device__ __forceinline__ void rw2_phase(const Ctx& c0) { const Ctx c = fresh(c0);
;     ...
;         const int vt = w;
;         GAS bf16* S0B = (GAS bf16*)(ws + WS_S0B) + (size_t)h * 128 * 4096 + (16 * vt + l15) * 64 + 4 * q; GAS bf16* XTB = (GAS bf16*)(ws + WS_XTB) + (size_t)h * 128 * 4096 + (16 * vt + l15) * 64 + 4 * q;
;         f32x4 S[4];
; #pragma unroll
;         for (int kt = 0; kt < 4; ++kt) S[kt] = (f32x4){0.f, 0.f, 0.f, 0.f};
;         RW2_BAR();
.LBB0_2421:
	s_and_b64 vcc, exec, s[2:3]
	s_cbranch_vccz .LBB0_2487
	v_readlane_b32 s0, v254, 5
	v_readlane_b32 s1, v254, 6
	s_mov_b32 s5, s95
	s_mov_b32 s1, s0
	s_mov_b32 s2, s94
	s_mov_b32 s0, s90
	s_waitcnt vmcnt(0)
	v_mov_b32_e32 v2, 0x22600
	v_mbcnt_lo_u32_b32 v0, -1, 0
	v_mbcnt_hi_u32_b32 v0, -1, v0
	ds_read2_b32 v[2:3], v2 offset0:70 offset1:71
	s_mov_b64 s[6:7], -1
	s_cmp_lt_i32 s5, 4
	v_lshlrev_b32_e32 v82, 4, v0
	s_waitcnt lgkmcnt(0)
	v_readfirstlane_b32 s2, v2
	v_readfirstlane_b32 s3, v3
	s_cbranch_scc0 .LBB0_2426
	v_lshlrev_b32_e32 v2, 6, v0
	v_and_b32_e32 v4, 0x3c0, v2
	v_ashrrev_i32_e32 v2, 2, v0
	s_ashr_i32 s1, s0, 31
	v_and_b32_e32 v2, -4, v2
	v_ashrrev_i32_e32 v3, 31, v2
	s_lshl_b64 s[6:7], s[0:1], 20
	v_lshl_or_b32 v4, s5, 10, v4
	s_barrier
	v_lshlrev_b32_e32 v83, 2, v2
	v_lshl_add_u64 v[2:3], v[2:3], 1, s[6:7]
	v_ashrrev_i32_e32 v5, 31, v4
	v_lshl_add_u64 v[2:3], v[4:5], 1, v[2:3]
	v_mov_b32_e32 v86, 0
	s_lshl_b32 s8, s5, 9
	v_lshlrev_b32_e32 v0, 3, v0
	v_lshl_add_u64 v[84:85], s[2:3], 0, v[2:3]
	s_mov_b32 s1, 0
	s_mov_b64 s[6:7], 0
	v_mov_b32_e32 v87, v86
	v_mov_b32_e32 v88, v86
	v_mov_b32_e32 v89, v86
	v_mov_b32_e32 v90, v86
	v_mov_b32_e32 v91, v86
	v_mov_b32_e32 v92, v86
	v_mov_b32_e32 v93, v86
	v_mov_b32_e32 v94, v86
	v_mov_b32_e32 v95, v86
	v_mov_b32_e32 v96, v86
	v_mov_b32_e32 v97, v86
	v_mov_b32_e32 v98, v86
	v_mov_b32_e32 v99, v86
	v_mov_b32_e32 v100, v86
	v_mov_b32_e32 v101, v86
	v_mbcnt_lo_u32_b32 v149, -1, 0
	v_mbcnt_hi_u32_b32 v149, -1, v149
	s_mul_i32 s45, s5, 0x900
	s_add_i32 s45, s45, 0x1f800
	s_lshl_b32 s44, s5, 11
	v_and_b32_e32 v146, 15, v149
	v_mul_u32_u24_e32 v146, 0x90, v146
	v_lshrrev_b32_e32 v150, 4, v149
	v_lshl_add_u32 v146, v150, 3, v146
	v_add_u32_e32 v146, s45, v146
	v_lshrrev_b32_e32 v147, 3, v149
	v_mul_u32_u24_e32 v147, 0x90, v147
	v_and_b32_e32 v150, 7, v149
	v_lshl_add_u32 v147, v150, 4, v147
	v_add_u32_e32 v147, s45, v147
	v_add_u32_e32 v148, s44, v82
	s_lshl_b32 s46, s0, 20
	s_add_u32 s40, s2, s46
	s_addc_u32 s41, s3, 0
	s_add_u32 s40, s40, 0x67e00000
	s_addc_u32 s41, s41, 0
	s_add_u32 s42, s40, 0x1000000
	s_addc_u32 s43, s41, 0
; #define GAS __attribute__((address_space(1)))
; #define LAS __attribute__((address_space(3)))
; __device__ __forceinline__ void rw2_phase(const Ctx& c0) { const Ctx c = fresh(c0);
;     ...
;         for (int n = 0; n < 128; ++n) {
;             const LAS unsigned char* sl = ring + (n % 5) * SLOT;
;             u32x4 caf[8], cbf[8]; f32x4 cvk[4], cpl[4];
; #pragma unroll
;             for (int f = 0; f < 8; ++f) caf[f] = *(const LAS u32x4*)(sl + f * 1024 + lane * 16);
; #pragma unroll
;             for (int f = 0; f < 8; ++f) cbf[f] = *(const LAS u32x4*)(sl + 8192 + f * 1024 + lane * 16);
; #pragma unroll
;             for (int kt = 0; kt < 4; ++kt) { const u32x2 vk = *(const LAS u32x2*)(sl + 16384 + (kt * 4 + vt) * 512 + lane * 8); cvk[kt] = (f32x4){bf_lo(vk.x), bf_hi(vk.x), bf_lo(vk.y), bf_hi(vk.y)};
;                 cpl[kt] = *(const LAS f32x4*)(sl + 24 * 1024 + (16 * kt + 4 * q) * 4); }
;             u32x4 sb[2];
; #pragma unroll
;             for (int s2 = 0; s2 < 2; ++s2) { sb[s2].x = cvt_pk_bf16(S[2 * s2][0], S[2 * s2][1]); sb[s2].y = cvt_pk_bf16(S[2 * s2][2], S[2 * s2][3]); sb[s2].z = cvt_pk_bf16(S[2 * s2 + 1][0], S[2 * s2 + 1][1]); sb[s2].w = cvt_pk_bf16(S[2 * s2 + 1][2], S[2 * s2 + 1][3]);
;                 *(GAS u32x2*)(S0B + (size_t)n * 4096 + 32 * s2) = (u32x2){sb[s2].x, sb[s2].y}; *(GAS u32x2*)(S0B + (size_t)n * 4096 + 32 * s2 + 16) = (u32x2){sb[s2].z, sb[s2].w}; }
;             f32x4 X[4];
; #pragma unroll
;             for (int mt = 0; mt < 4; ++mt) { X[mt] = (f32x4){0.f, 0.f, 0.f, 0.f};
; #pragma unroll
;                 for (int s2 = 0; s2 < 2; ++s2) X[mt] = __builtin_amdgcn_mfma_f32_16x16x32_bf16(__builtin_bit_cast(bf16x8, caf[mt * 2 + s2]), __builtin_bit_cast(bf16x8, sb[s2]), X[mt], 0, 0, 0); }
;             u32x4 xb[2];
; #pragma unroll
;             for (int s2 = 0; s2 < 2; ++s2) { xb[s2].x = cvt_pk_bf16(X[2 * s2][0], X[2 * s2][1]); xb[s2].y = cvt_pk_bf16(X[2 * s2][2], X[2 * s2][3]); xb[s2].z = cvt_pk_bf16(X[2 * s2 + 1][0], X[2 * s2 + 1][1]); xb[s2].w = cvt_pk_bf16(X[2 * s2 + 1][2], X[2 * s2 + 1][3]);
;                 *(GAS u32x2*)(XTB + (size_t)n * 4096 + 32 * s2) = (u32x2){xb[s2].x, xb[s2].y}; *(GAS u32x2*)(XTB + (size_t)n * 4096 + 32 * s2 + 16) = (u32x2){xb[s2].z, xb[s2].w}; }
; #pragma unroll
;             for (int kt = 0; kt < 4; ++kt) { f32x4 a = S[kt] + cvk[kt];
; #pragma unroll
.LBB0_2424:
	s_mul_i32 s9, s1, 0xcd
	s_bfe_u32 s9, s9, 0x6000a
	s_mul_i32 s9, s9, 5
	s_sub_i32 s9, s1, s9
	s_and_b32 s9, s9, 0xff
	s_mulk_i32 s9, 0x6400
	s_addk_i32 s9, 0x400
	s_add_i32 s10, s9, s8
	v_add_u32_e32 v6, s9, v82
	v_add_u32_e32 v42, s10, v0
	ds_read_b128 v[50:53], v6
	ds_read_b128 v[54:57], v6 offset:1024
	ds_read_b128 v[58:61], v6 offset:2048
	ds_read_b128 v[62:65], v6 offset:3072
	ds_read_b128 v[66:69], v6 offset:4096
	ds_read_b128 v[70:73], v6 offset:5120
	ds_read_b128 v[74:77], v6 offset:6144
	ds_read_b128 v[78:81], v6 offset:7168
	ds_read_b128 v[26:29], v6 offset:8192
	ds_read_b128 v[30:33], v6 offset:9216
	ds_read_b128 v[18:21], v6 offset:10240
	ds_read_b128 v[22:25], v6 offset:11264
	ds_read_b128 v[10:13], v6 offset:12288
	ds_read_b128 v[14:17], v6 offset:13312
	ds_read_b128 v[2:5], v6 offset:14336
	ds_read_b128 v[6:9], v6 offset:15360
	ds_read2st64_b64 v[34:37], v42 offset0:32 offset1:36
	v_add_u32_e32 v118, s9, v83
	ds_read_b128 v[46:49], v118 offset:24576
	v_cvt_pk_bf16_f32 v119, v88, v89
	v_cvt_pk_bf16_f32 v120, v90, v91
	s_waitcnt lgkmcnt(1)
	v_lshlrev_b32_e32 v108, 16, v34
	v_and_b32_e32 v109, 0xffff0000, v34
	v_lshlrev_b32_e32 v116, 16, v35
	v_and_b32_e32 v117, 0xffff0000, v35
	v_lshlrev_b32_e32 v106, 16, v36
	v_and_b32_e32 v107, 0xffff0000, v36
	v_lshlrev_b32_e32 v114, 16, v37
	v_and_b32_e32 v115, 0xffff0000, v37
	ds_read_b128 v[38:41], v118 offset:24640
	ds_read2st64_b64 v[34:37], v42 offset0:40 offset1:44
	ds_read_b128 v[42:45], v118 offset:24704
	v_cvt_pk_bf16_f32 v121, v92, v93
	v_cvt_pk_bf16_f32 v122, v94, v95
	v_cvt_pk_bf16_f32 v123, v96, v97
	s_waitcnt lgkmcnt(1)
	v_lshlrev_b32_e32 v104, 16, v34
	v_and_b32_e32 v105, 0xffff0000, v34
	v_lshlrev_b32_e32 v112, 16, v35
	v_and_b32_e32 v113, 0xffff0000, v35
	v_lshlrev_b32_e32 v102, 16, v36
	v_and_b32_e32 v103, 0xffff0000, v36
	v_lshlrev_b32_e32 v110, 16, v37
	v_and_b32_e32 v111, 0xffff0000, v37
	ds_read_b128 v[34:37], v118 offset:24768
	v_cvt_pk_bf16_f32 v118, v86, v87
	v_cvt_pk_bf16_f32 v124, v98, v99
	v_cvt_pk_bf16_f32 v125, v100, v101
	v_mfma_f32_16x16x32_bf16 v[50:53], v[50:53], v[118:121], 0
	ds_write2_b64 v146, v[118:119], v[120:121] offset1:4
	ds_write2_b64 v146, v[122:123], v[124:125] offset0:8 offset1:12
	ds_read_b128 v[130:133], v147
	v_mfma_f32_16x16x32_bf16 v[50:53], v[54:57], v[122:125], v[50:53]
	s_nop 0
	ds_read_b128 v[134:137], v147 offset:1152
	s_nop 0
	v_mfma_f32_16x16x32_bf16 v[54:57], v[58:61], v[118:121], 0
	s_nop 0
	s_nop 0
	s_nop 1
	v_cvt_pk_bf16_f32 v50, v50, v51
	v_cvt_pk_bf16_f32 v51, v52, v53
	v_mfma_f32_16x16x32_bf16 v[58:61], v[66:69], v[118:121], 0
	s_nop 0
	s_nop 0
	s_nop 0
	v_mfma_f32_16x16x32_bf16 v[54:57], v[62:65], v[122:125], v[54:57]
	s_nop 0
	s_add_i32 s1, s1, 1
	v_mfma_f32_16x16x32_bf16 v[58:61], v[70:73], v[122:125], v[58:61]
	s_add_u32 s6, s6, 0x2000
	s_nop 3
	v_cvt_pk_bf16_f32 v52, v54, v55
	v_cvt_pk_bf16_f32 v53, v56, v57
	v_mfma_f32_16x16x32_bf16 v[62:65], v[74:77], v[118:121], 0
	ds_write2_b64 v146, v[50:51], v[52:53] offset1:4
	s_nop 0
	v_cvt_pk_bf16_f32 v54, v58, v59
	v_cvt_pk_bf16_f32 v55, v60, v61
	v_mfma_f32_16x16x32_bf16 v[62:65], v[78:81], v[122:125], v[62:65]
	v_add_f32_e64 v60, v88, v116
	v_add_f32_e64 v61, v89, v117
	v_pk_add_f32 v[58:59], v[86:87], v[108:109]
	s_addc_u32 s7, s7, 0
	s_cmp_eq_u32 s6, 0x100000
	v_mfma_f32_16x16x32_bf16 v[26:29], v[26:29], v[50:53], v[58:61]
	s_nop 1
	v_cvt_pk_bf16_f32 v56, v62, v63
	v_cvt_pk_bf16_f32 v57, v64, v65
	ds_write2_b64 v146, v[54:55], v[56:57] offset0:8 offset1:12
	ds_read_b128 v[138:141], v147
	v_mfma_f32_16x16x32_bf16 v[26:29], v[30:33], v[54:57], v[26:29]
	ds_read_b128 v[142:145], v147 offset:1152
	s_waitcnt lgkmcnt(0)
	s_barrier
	global_store_dwordx4 v148, v[130:133], s[40:41]
	global_store_dwordx4 v148, v[134:137], s[40:41] offset:1024
	global_store_dwordx4 v148, v[138:141], s[42:43]
	global_store_dwordx4 v148, v[142:145], s[42:43] offset:1024
	v_add_u32_e32 v148, 0x2000, v148
	s_nop 1
	v_pk_mul_f32 v[88:89], v[48:49], v[28:29]
	v_pk_mul_f32 v[86:87], v[46:47], v[26:27]
	v_pk_add_f32 v[28:29], v[92:93], v[114:115]
	v_pk_add_f32 v[26:27], v[90:91], v[106:107]
	s_nop 1
	v_mfma_f32_16x16x32_bf16 v[18:21], v[18:21], v[50:53], v[26:29]
	v_mfma_f32_16x16x32_bf16 v[18:21], v[22:25], v[54:57], v[18:21]
	s_nop 7
	v_pk_mul_f32 v[92:93], v[40:41], v[20:21]
	v_pk_mul_f32 v[90:91], v[38:39], v[18:19]
	v_pk_add_f32 v[20:21], v[96:97], v[112:113]
	v_pk_add_f32 v[18:19], v[94:95], v[104:105]
	s_nop 1
	v_mfma_f32_16x16x32_bf16 v[10:13], v[10:13], v[50:53], v[18:21]
	v_mfma_f32_16x16x32_bf16 v[10:13], v[14:17], v[54:57], v[10:13]
	s_waitcnt lgkmcnt(1)
	s_nop 6
	v_pk_mul_f32 v[96:97], v[44:45], v[12:13]
	v_pk_mul_f32 v[94:95], v[42:43], v[10:11]
	v_pk_add_f32 v[12:13], v[100:101], v[110:111]
	v_pk_add_f32 v[10:11], v[98:99], v[102:103]
	s_nop 1
	v_mfma_f32_16x16x32_bf16 v[2:5], v[2:5], v[50:53], v[10:13]
	v_mfma_f32_16x16x32_bf16 v[2:5], v[6:9], v[54:57], v[2:5]
	s_waitcnt lgkmcnt(0)
	s_nop 6
	v_pk_mul_f32 v[100:101], v[36:37], v[4:5]
	v_pk_mul_f32 v[98:99], v[34:35], v[2:3]
	s_cbranch_scc0 .LBB0_2424
	s_mov_b64 s[6:7], 0
